# attention: drop the static wave-priority split (all 8 waves at priority 0)
# baseline (speedup 1.0000x reference)
.LBB0_529:
	v_readfirstlane_b32 s2, v214
	s_cmpk_gt_i32 s2, 0xff
	s_cbranch_scc0 .LBB0_531
	s_setprio 0
